# v109 + final norm phase: g held in registers (no per-row L2 loads / store-ack waits) and next row's x prefetched one row ahead
# speedup vs baseline: 1.0061x; 1.0021x over previous
.LBB0_76:
.LBB0_77:
	v_mov_b32_e32 v166, v155
	s_mov_b64 s[22:23], -1
	s_mov_b64 s[0:1], 0
	s_cmp_lt_i32 s12, 29
	s_mov_b64 s[2:3], 0
	s_cbranch_scc1 .LBB0_84
	s_cmp_eq_u32 s12, 29
	s_mov_b64 s[2:3], -1
	s_cbranch_scc0 .LBB0_83
	v_ashrrev_i32_e32 v0, 6, v166
	v_readlane_b32 s2, v252, 17
	s_nop 1
	v_add_u32_e32 v2, s2, v0
	v_cmp_gt_i32_e32 vcc, s40, v2
	s_and_saveexec_b64 s[2:3], vcc
	s_cbranch_execz .LBB0_82
	v_and_b32_e32 v0, 64, v220
	v_add_u32_e32 v0, 64, v0
	v_xor_b32_e32 v3, 32, v220
	v_cmp_lt_i32_e32 vcc, v3, v0
	s_load_dword s4, s[96:97], 0x0
	v_readlane_b32 s56, v254, 4
	v_cndmask_b32_e32 v3, v220, v3, vcc
	v_lshlrev_b32_e32 v8, 2, v3
	v_xor_b32_e32 v3, 16, v220
	v_cmp_lt_i32_e32 vcc, v3, v0
	v_readlane_b32 s57, v254, 5
	v_readlane_b32 s58, v254, 6
	v_cndmask_b32_e32 v3, v220, v3, vcc
	v_lshlrev_b32_e32 v9, 2, v3
	v_xor_b32_e32 v3, 8, v220
	v_cmp_lt_i32_e32 vcc, v3, v0
	v_readlane_b32 s59, v254, 7
	v_readlane_b32 s60, v254, 8
	v_cndmask_b32_e32 v3, v220, v3, vcc
	v_lshlrev_b32_e32 v10, 2, v3
	v_xor_b32_e32 v3, 4, v220
	v_cmp_lt_i32_e32 vcc, v3, v0
	v_readlane_b32 s61, v254, 9
	v_readlane_b32 s62, v254, 10
	v_cndmask_b32_e32 v3, v220, v3, vcc
	v_lshlrev_b32_e32 v11, 2, v3
	v_xor_b32_e32 v3, 2, v220
	v_cmp_lt_i32_e32 vcc, v3, v0
	v_readlane_b32 s63, v254, 11
	v_readlane_b32 s64, v254, 12
	v_cndmask_b32_e32 v3, v220, v3, vcc
	v_lshlrev_b32_e32 v12, 2, v3
	v_xor_b32_e32 v3, 1, v220
	v_cmp_lt_i32_e32 vcc, v3, v0
	v_readlane_b32 s65, v254, 13
	v_readlane_b32 s66, v254, 14
	v_cndmask_b32_e32 v0, v220, v3, vcc
	v_lshlrev_b32_e32 v13, 2, v0
	v_lshlrev_b32_e32 v0, 4, v166
	v_and_b32_e32 v0, 0x3f0, v0
	v_readlane_b32 s67, v254, 15
	v_readlane_b32 s68, v254, 16
	v_readlane_b32 s69, v254, 17
	v_readlane_b32 s70, v254, 18
	v_readlane_b32 s71, v254, 19
	v_lshl_add_u64 v[4:5], s[68:69], 0, v[0:1]
	s_waitcnt lgkmcnt(0)
	s_lshl_b32 s4, s4, 3
	v_lshl_add_u64 v[6:7], s[70:71], 0, v[0:1]
	v_readlane_b32 s56, v252, 35
	v_readlane_b32 s57, v252, 36
	v_readlane_b32 s58, v252, 37
	v_readlane_b32 s59, v252, 38
	v_readlane_b32 s66, v252, 45
	v_readlane_b32 s67, v252, 46
	v_readlane_b32 s70, v252, 49
	v_readlane_b32 s71, v252, 50
	s_mov_b64 s[22:23], 0
	v_readlane_b32 s60, v252, 39
	v_readlane_b32 s61, v252, 40
	v_readlane_b32 s62, v252, 41
	v_readlane_b32 s63, v252, 42
	v_readlane_b32 s64, v252, 43
	v_readlane_b32 s65, v252, 44
	v_readlane_b32 s68, v252, 47
	v_readlane_b32 s69, v252, 48
	v_ashrrev_i32_e32 v3, 31, v2
	v_lshlrev_b64 v[98:99], 12, v[2:3]
	v_lshl_add_u64 v[96:97], v[6:7], 0, v[98:99]
	global_load_dwordx4 v[80:83], v[96:97], off nt
	global_load_dwordx4 v[84:87], v[96:97], off offset:1024 nt
	global_load_dwordx4 v[88:91], v[96:97], off offset:2048 nt
	global_load_dwordx4 v[92:95], v[96:97], off offset:3072 nt
	global_load_dwordx4 v[102:105], v[4:5], off
	global_load_dwordx4 v[106:109], v[4:5], off offset:1024
	global_load_dwordx4 v[110:113], v[4:5], off offset:2048
	global_load_dwordx4 v[118:121], v[4:5], off offset:3072
	s_waitcnt vmcnt(0)
.LBB0_81:
	v_ashrrev_i32_e32 v3, 31, v2
	v_lshlrev_b64 v[14:15], 12, v[2:3]
	v_lshl_add_u64 v[34:35], v[6:7], 0, v[14:15]
	s_waitcnt vmcnt(4)
	v_mov_b64_e32 v[14:15], v[80:81]
	v_mov_b64_e32 v[16:17], v[82:83]
	v_mov_b64_e32 v[18:19], v[84:85]
	v_mov_b64_e32 v[20:21], v[86:87]
	v_mov_b64_e32 v[22:23], v[88:89]
	v_mov_b64_e32 v[24:25], v[90:91]
	v_mov_b64_e32 v[26:27], v[92:93]
	v_mov_b64_e32 v[28:29], v[94:95]
	v_add_u32_e32 v2, s4, v2
	v_cmp_gt_i32_e32 vcc, s40, v2
	s_and_saveexec_b64 s[98:99], vcc
	v_ashrrev_i32_e32 v3, 31, v2
	v_lshlrev_b64 v[98:99], 12, v[2:3]
	v_lshl_add_u64 v[96:97], v[6:7], 0, v[98:99]
	global_load_dwordx4 v[80:83], v[96:97], off nt
	global_load_dwordx4 v[84:87], v[96:97], off offset:1024 nt
	global_load_dwordx4 v[88:91], v[96:97], off offset:2048 nt
	global_load_dwordx4 v[92:95], v[96:97], off offset:3072 nt
	s_mov_b64 exec, s[98:99]
	v_mov_b32_e32 v38, v15
	v_mov_b32_e32 v39, v19
	v_mov_b32_e32 v36, v14
	v_mov_b32_e32 v37, v18
	v_mov_b32_e32 v46, v23
	v_mov_b32_e32 v47, v27
	v_pk_mul_f32 v[38:39], v[38:39], v[38:39]
	v_mov_b32_e32 v40, v16
	v_mov_b32_e32 v41, v20
	v_mov_b32_e32 v44, v22
	v_mov_b32_e32 v45, v26
	v_pk_mul_f32 v[46:47], v[46:47], v[46:47]
	v_pk_fma_f32 v[36:37], v[36:37], v[36:37], v[38:39]
	v_mov_b32_e32 v42, v17
	v_mov_b32_e32 v43, v21
	v_mov_b32_e32 v48, v24
	v_mov_b32_e32 v49, v28
	v_pk_fma_f32 v[38:39], v[44:45], v[44:45], v[46:47]
	v_pk_fma_f32 v[36:37], v[40:41], v[40:41], v[36:37]
	v_mov_b32_e32 v50, v25
	v_mov_b32_e32 v51, v29
	v_pk_fma_f32 v[38:39], v[48:49], v[48:49], v[38:39]
	v_pk_fma_f32 v[36:37], v[42:43], v[42:43], v[36:37]
	v_pk_fma_f32 v[38:39], v[50:51], v[50:51], v[38:39]
	v_add_f32_e32 v0, v36, v37
	v_add_f32_e32 v0, v0, v38
	v_add_f32_e32 v0, v0, v39
	ds_bpermute_b32 v3, v8, v0
	s_waitcnt lgkmcnt(0)
	v_add_f32_e32 v0, v0, v3
	ds_bpermute_b32 v3, v9, v0
	s_waitcnt lgkmcnt(0)
	v_add_f32_e32 v0, v0, v3
	ds_bpermute_b32 v3, v10, v0
	s_waitcnt lgkmcnt(0)
	v_add_f32_e32 v0, v0, v3
	ds_bpermute_b32 v3, v11, v0
	s_waitcnt lgkmcnt(0)
	v_add_f32_e32 v0, v0, v3
	ds_bpermute_b32 v3, v12, v0
	s_waitcnt lgkmcnt(0)
	v_add_f32_e32 v0, v0, v3
	ds_bpermute_b32 v3, v13, v0
	s_waitcnt lgkmcnt(0)
	v_add_f32_e32 v0, v0, v3
	v_fmamk_f32 v0, v0, 0x3a800000, v218
	v_mul_f32_e32 v3, 0x4b800000, v0
	v_cmp_gt_f32_e32 vcc, s13, v0
	s_nop 1
	v_cndmask_b32_e32 v0, v0, v3, vcc
	v_rsq_f32_e32 v0, v0
	s_nop 0
	v_mul_f32_e32 v3, 0x45800000, v0
	v_cndmask_b32_e32 v0, v0, v3, vcc
	v_pk_mul_f32 v[14:15], v[14:15], v[0:1] op_sel_hi:[1,0]
	v_pk_mul_f32 v[16:17], v[16:17], v[0:1] op_sel_hi:[1,0]
	v_pk_mul_f32 v[18:19], v[18:19], v[0:1] op_sel_hi:[1,0]
	v_pk_mul_f32 v[20:21], v[20:21], v[0:1] op_sel_hi:[1,0]
	v_pk_mul_f32 v[22:23], v[22:23], v[0:1] op_sel_hi:[1,0]
	v_pk_mul_f32 v[24:25], v[24:25], v[0:1] op_sel_hi:[1,0]
	v_pk_mul_f32 v[26:27], v[26:27], v[0:1] op_sel_hi:[1,0]
	v_pk_mul_f32 v[28:29], v[28:29], v[0:1] op_sel_hi:[1,0]
	v_pk_mul_f32 v[14:15], v[102:103], v[14:15]
	v_pk_mul_f32 v[16:17], v[104:105], v[16:17]
	v_pk_mul_f32 v[18:19], v[106:107], v[18:19]
	v_pk_mul_f32 v[20:21], v[108:109], v[20:21]
	v_pk_mul_f32 v[22:23], v[110:111], v[22:23]
	v_pk_mul_f32 v[24:25], v[112:113], v[24:25]
	v_pk_mul_f32 v[26:27], v[118:119], v[26:27]
	v_pk_mul_f32 v[28:29], v[120:121], v[28:29]
	v_cmp_lt_i32_e32 vcc, s14, v2
	s_or_b64 s[22:23], vcc, s[22:23]
	s_nop 0
	global_store_dwordx4 v[34:35], v[14:17], off nt
	global_store_dwordx4 v[34:35], v[18:21], off offset:1024 nt
	global_store_dwordx4 v[34:35], v[22:25], off offset:2048 nt
	global_store_dwordx4 v[34:35], v[26:29], off offset:3072 nt
	s_andn2_b64 exec, exec, s[22:23]
	s_cbranch_execnz .LBB0_81

.LBB0_98:
	s_or_b64 exec, exec, s[0:1]
	v_readlane_b32 s0, v253, 61
	s_waitcnt lgkmcnt(0)
	s_barrier
	v_mov_b32_e32 v0, s0
	ds_read_b32 v0, v0
	s_mov_b64 s[0:1], -1
	s_waitcnt lgkmcnt(0)
	v_cmp_le_i32_e32 vcc, s94, v0
	v_readfirstlane_b32 s46, v0
	s_cbranch_vccnz .LBB0_93
	s_cmpk_lt_i32 s46, 0x100
	s_cselect_b64 s[0:1], -1, 0
	v_mov_b32_e32 v168, v155
	s_and_b64 vcc, exec, s[0:1]
	s_cbranch_vccnz .LBB0_244
	s_cmp_lt_i32 s46, s37
	s_cselect_b64 s[0:1], -1, 0
	s_cmp_ge_i32 s46, s41
	s_cselect_b64 s[2:3], -1, 0
	s_or_b64 s[2:3], s[0:1], s[2:3]
	s_mov_b64 s[0:1], -1
	s_and_b64 vcc, exec, s[2:3]
	s_cbranch_vccz .LBB0_244
	s_cmpk_gt_u32 s46, 0x2ff
	s_cbranch_scc0 .LBB0_227
	s_cmpk_gt_u32 s46, 0x4ff
	s_cbranch_scc0 .LBB0_158
	s_cmp_ge_i32 s46, s37
	s_cbranch_scc0 .LBB0_153
	s_cmp_ge_i32 s46, s92
	s_cbranch_scc0 .LBB0_138
	s_cmp_ge_i32 s46, s93
	s_cbranch_scc0 .LBB0_122
	s_sub_i32 s10, s46, s93
	v_readlane_b32 s32, v254, 57
	s_add_i32 s32, s32, 1
	s_sub_u32 s98, s96, 0xd0
	s_subb_u32 s99, s97, 0
	v_readfirstlane_b32 s58, v155
	s_lshr_b32 s58, s58, 6
	v_and_b32_e32 v102, 63, v155
	v_lshlrev_b32_e32 v103, 4, v102
	s_cmp_lt_u32 s10, 0x80
	s_cbranch_scc0 .Lmy_tm_s1
	s_load_dwordx2 s[72:73], s[98:99], 0x40
	s_lshr_b32 s11, s10, 3
	s_and_b32 s13, s10, 7
	s_mul_i32 s20, s32, 0x900000
	s_add_u32 s20, s20, 0x400
	s_mul_i32 s56, s32, 0x500000
	s_add_u32 s56, s56, 0x500000
	s_movk_i32 s4, 0x2400
	s_movk_i32 s6, 0x800
	s_mov_b32 s57, 13
	s_branch .Lmy_tm_sd
	s_nop 0
	s_nop 0
	s_nop 0
	s_nop 0
	s_nop 0
	s_nop 0
	s_nop 0
	s_nop 0
	s_nop 0
	s_nop 0
	s_nop 0
	s_nop 0
	s_nop 0
	s_nop 0
	s_nop 0
	s_nop 0
	s_nop 0
	s_nop 0
	s_nop 0
	s_nop 0
	s_nop 0
	s_nop 0
	s_nop 0
	s_nop 0
	s_nop 0
	s_nop 0
	s_nop 0
	s_nop 0
	s_nop 0
	s_nop 0
	s_nop 0
	s_nop 0
	s_nop 0
	s_nop 0
	s_nop 0
	s_nop 0
	s_nop 0
	s_nop 0
	s_nop 0
.Lmy_tm_s1:
	s_cmp_lt_u32 s10, 0xc0
	s_cbranch_scc0 .Lmy_tm_s2
	s_load_dwordx2 s[72:73], s[98:99], 0x48
	s_sub_i32 s10, s10, 0x80
	s_lshr_b32 s11, s10, 2
	s_and_b32 s13, s10, 3
	s_lshl_b32 s20, s32, 22
	s_lshl_b32 s56, s32, 21
	s_add_u32 s56, s56, 0x1800000
	s_movk_i32 s4, 0x1000
	s_movk_i32 s6, 0x800
	s_mov_b32 s57, 13
	s_branch .Lmy_tm_sd
